# same priority scheme also around the three LDS-DMA GEMM k-loops of the merge phase
# baseline (speedup 1.0000x reference)
; template <int NJ, bool SPLIT = false>
; __device__ __forceinline__ void gemm_tile_dma(const f16* __restrict__ A, int lda, const f16* __restrict__ Bt, int ldb,
;                                               int K, f32x4 (&acc)[4][NJ], f16* sA, const int tid) {
;   constexpr int DSTAGE = 16384;
;   const int lane = tid & 63;
;   const int wave = __builtin_amdgcn_readfirstlane(tid >> 6);
;   const int wm = wave >> 1, wn = wave & 1;
;   const int lr = lane >> 3, ls = lane & 7;
;   const int ra = wave * 32 + lr;
;   const int rb = wave * (NJ * 8) + lr;
;   const f16* asrc = A + (size_t)ra * lda + ((ls ^ (ra & 7)) * 8);
;   const f16* bsrc = Bt + ((ls ^ (rb & 7)) * 8);
;   f16* adst = sA + (wave * 32) * 64;
;   f16* bdst = sA + 8192 + (wave * (NJ * 8)) * 64;
;   const int lq = lane & 15, g = lane >> 4;
;   const int rdA = (wm * 64 + lq) * 64;
;   const int rdB = 8192 + (wn * (NJ * 16) + lq) * 64;
;   const int sw0 = ((0 + g) ^ (lq & 7)) * 8, sw1 = ((4 + g) ^ (lq & 7)) * 8;
;     ...
;   __syncthreads();
;   D_STAGE(0, 0)
;   asm volatile("s_waitcnt vmcnt(0)" ::: "memory");
;   __syncthreads();
;   int cur = 0;
; __device__ __forceinline__ void phase_g2(const Params& p, int l, f16* smem) {
;     ...
;     for (int x = 0; x < 3; ++x) {
;       f16x4 sg[4][4];
;       {
;         f32x4 ag[4][4];
;         zero_acc<4>(ag);
;         gemm_tile_dma<4>(HP + (size_t)m0 * DM, DM, WG + (size_t)(x * DM + n0) * DM, DM, DM, ag, sA, TIDX(p));
.LBB0_1115:
	s_ashr_i32 s15, s14, 31
	s_lshl_b64 s[16:17], s[14:15], 11
	s_lshl_b32 s15, s9, 10
	v_readfirstlane_b32 s20, v156
	s_add_i32 s18, s15, s8
	s_ashr_i32 s15, s20, 6
	s_lshl_b32 s21, s15, 5
	v_or_b32_e32 v0, s21, v157
	v_ashrrev_i32_e32 v1, 31, v0
	v_lshlrev_b64 v[2:3], 11, v[0:1]
	s_lshl_b32 s15, s15, 12
	v_lshl_add_u64 v[4:5], v[110:111], 0, v[2:3]
	s_mov_b32 m0, s15
	s_barrier
	global_load_lds_dwordx4 v[4:5], off
	v_lshl_add_u64 v[6:7], v[4:5], 0, s[66:67]
	s_or_b32 m0, s15, 0x400
	s_ashr_i32 s19, s18, 31
	global_load_lds_dwordx4 v[6:7], off
	v_lshl_add_u64 v[6:7], v[4:5], 0, s[92:93]
	s_or_b32 m0, s15, 0x800
	s_lshl_b64 s[18:19], s[18:19], 11
	global_load_lds_dwordx4 v[6:7], off
	v_lshl_add_u64 v[4:5], v[4:5], 0, s[78:79]
	s_or_b32 m0, s15, 0xc00
	s_lshr_b32 s24, s20, 1
	global_load_lds_dwordx4 v[4:5], off
	v_lshl_add_u64 v[4:5], v[72:73], 0, s[18:19]
	s_add_i32 m0, s15, 0x4000
	v_lshl_add_u64 v[6:7], v[4:5], 0, v[2:3]
	global_load_lds_dwordx4 v[6:7], off
	v_or_b32_e32 v6, 8, v0
	v_ashrrev_i32_e32 v7, 31, v6
	v_lshlrev_b64 v[6:7], 11, v[6:7]
	v_lshl_add_u64 v[6:7], v[4:5], 0, v[6:7]
	s_add_i32 m0, s15, 0x4400
	s_and_b32 s24, s24, 0x1ffffc0
	global_load_lds_dwordx4 v[6:7], off
	v_or_b32_e32 v6, 16, v0
	v_ashrrev_i32_e32 v7, 31, v6
	v_or_b32_e32 v0, 24, v0
	v_lshlrev_b64 v[6:7], 11, v[6:7]
	v_ashrrev_i32_e32 v1, 31, v0
	v_lshl_add_u64 v[6:7], v[4:5], 0, v[6:7]
	s_add_i32 m0, s15, 0x4800
	v_lshlrev_b64 v[0:1], 11, v[0:1]
	global_load_lds_dwordx4 v[6:7], off
	v_lshl_add_u64 v[0:1], v[4:5], 0, v[0:1]
	s_add_i32 m0, s15, 0x4c00
	v_lshl_add_u64 v[4:5], v[76:77], 0, s[16:17]
	global_load_lds_dwordx4 v[0:1], off
	v_or_b32_e32 v0, s21, v161
	v_ashrrev_i32_e32 v1, 31, v0
	v_lshlrev_b64 v[0:1], 11, v[0:1]
	v_lshl_add_u64 v[118:119], v[4:5], 0, v[0:1]
	v_or_b32_e32 v0, s21, v162
	v_ashrrev_i32_e32 v1, 31, v0
	v_lshlrev_b64 v[0:1], 11, v[0:1]
	v_lshl_add_u64 v[120:121], v[4:5], 0, v[0:1]
	v_or_b32_e32 v0, s21, v163
	s_waitcnt vmcnt(0)
	v_ashrrev_i32_e32 v1, 31, v0
	v_and_or_b32 v8, s20, 64, v158
	v_or_b32_e32 v9, s24, v158
	v_lshlrev_b64 v[0:1], 11, v[0:1]
	v_lshlrev_b32_e32 v128, 7, v9
	v_lshlrev_b32_e32 v129, 7, v8
	v_lshl_add_u64 v[122:123], v[4:5], 0, v[0:1]
	v_lshl_add_u64 v[124:125], v[4:5], 0, v[2:3]
	v_lshl_add_u64 v[126:127], v[116:117], 0, v[2:3]
	s_mov_b32 s18, 0
	s_mov_b32 s19, 0
	v_mov_b32_e32 v12, 0
	v_mov_b32_e32 v13, v168
	v_mov_b32_e32 v14, v168
	v_mov_b32_e32 v15, v168
	v_mov_b32_e32 v24, 0
	v_mov_b32_e32 v25, v168
	v_mov_b32_e32 v26, v168
	v_mov_b32_e32 v27, v168
	v_mov_b32_e32 v32, 0
	v_mov_b32_e32 v33, v168
	v_mov_b32_e32 v34, v168
	v_mov_b32_e32 v35, v168
	v_mov_b32_e32 v0, 0
	v_mov_b32_e32 v1, v168
	v_mov_b32_e32 v2, v168
	v_mov_b32_e32 v3, v168
	v_mov_b32_e32 v4, 0
	v_mov_b32_e32 v5, v168
	v_mov_b32_e32 v6, v168
	v_mov_b32_e32 v7, v168
	v_mov_b32_e32 v8, 0
	v_mov_b32_e32 v9, v168
	v_mov_b32_e32 v10, v168
	v_mov_b32_e32 v11, v168
	v_mov_b32_e32 v16, 0
	v_mov_b32_e32 v17, v168
	v_mov_b32_e32 v18, v168
	v_mov_b32_e32 v19, v168
	v_mov_b32_e32 v20, 0
	v_mov_b32_e32 v21, v168
	v_mov_b32_e32 v22, v168
	v_mov_b32_e32 v23, v168
	v_mov_b32_e32 v28, 0
	v_mov_b32_e32 v29, v168
	v_mov_b32_e32 v30, v168
	v_mov_b32_e32 v31, v168
	v_mov_b32_e32 v36, 0
	v_mov_b32_e32 v37, v168
	v_mov_b32_e32 v38, v168
	v_mov_b32_e32 v39, v168
	v_mov_b32_e32 v40, 0
	v_mov_b32_e32 v41, v168
	v_mov_b32_e32 v42, v168
	v_mov_b32_e32 v43, v168
	v_mov_b32_e32 v44, 0
	v_mov_b32_e32 v45, v168
	v_mov_b32_e32 v46, v168
	v_mov_b32_e32 v47, v168
	v_mov_b32_e32 v48, 0
	v_mov_b32_e32 v49, v168
	v_mov_b32_e32 v50, v168
	v_mov_b32_e32 v51, v168
	v_mov_b32_e32 v52, 0
	v_mov_b32_e32 v53, v168
	v_mov_b32_e32 v54, v168
	v_mov_b32_e32 v55, v168
	v_mov_b32_e32 v56, 0
	v_mov_b32_e32 v57, v168
	v_mov_b32_e32 v58, v168
	v_mov_b32_e32 v59, v168
	v_mov_b32_e32 v60, 0
	v_mov_b32_e32 v61, v168
	v_mov_b32_e32 v62, v168
	v_mov_b32_e32 v63, v168
	s_waitcnt vmcnt(0) lgkmcnt(0)
	s_barrier
	s_setprio 1
	s_bitcmp1_b32 s95, 8
	s_cbranch_scc0 .Lprio_g2_1117
	s_setprio 2

; __device__ __forceinline__ float sigmoidf_(float x) { return 1.0f / (1.0f + __expf(-x)); }
; template <int NJ, bool SPLIT = false>
; __device__ __forceinline__ void gemm_tile_dma(const f16* __restrict__ A, int lda, const f16* __restrict__ Bt, int ldb,
;                                               int K, f32x4 (&acc)[4][NJ], f16* sA, const int tid) {
;     ...
;   __syncthreads();
; __device__ __forceinline__ void phase_g2(const Params& p, int l, f16* smem) {
;     ...
; #pragma unroll
;         for (int i = 0; i < 4; ++i)
; #pragma unroll
;           for (int j = 0; j < 4; ++j)
; #pragma unroll
;             for (int r = 0; r < 4; ++r) sg[i][j][r] = (f16)sigmoidf_(ag[i][j][r]);
;       }
;       __builtin_amdgcn_sched_barrier(0);
;       const f16* wo = (const f16*)(p.ws + (x == 0 ? WT_RO_OFF : (x == 1 ? WT_PO_OFF : WT_NO_OFF)));
;       const int kx = x == 1 ? 256 : RD;
;       const int aoff = x == 0 ? 0 : (x == 1 ? RD : 640);
; #pragma unroll
;       for (int h = 0; h < 2; ++h) {
;         f32x4 ab[4][2];
;         zero_acc<2>(ab);
;         gemm_tile_dma<2, true>(BR + (size_t)m0 * DM + aoff, DM, wo + (size_t)(n0 + h * 32) * kx, kx, kx, ab, sA, TIDX(p));
.LBB0_1119:
	s_setprio 0
	s_nop 3
	v_mul_f32_e32 v0, 0xbfb8aa3b, v0
	v_exp_f32_e32 v124, v0
	v_mul_f32_e32 v0, 0xbfb8aa3b, v1
	v_exp_f32_e32 v125, v0
	v_mul_f32_e32 v0, 0xbfb8aa3b, v2
	v_exp_f32_e32 v122, v0
	v_mul_f32_e32 v0, 0xbfb8aa3b, v3
	v_exp_f32_e32 v123, v0
	v_mul_f32_e32 v0, 0xbfb8aa3b, v32
	v_exp_f32_e32 v120, v0
	v_mul_f32_e32 v0, 0xbfb8aa3b, v33
	v_exp_f32_e32 v121, v0
	v_mul_f32_e32 v0, 0xbfb8aa3b, v34
	v_exp_f32_e32 v118, v0
	v_mul_f32_e32 v0, 0xbfb8aa3b, v35
	v_exp_f32_e32 v119, v0
	v_mul_f32_e32 v0, 0xbfb8aa3b, v24
	v_exp_f32_e32 v209, v0
	v_mul_f32_e32 v0, 0xbfb8aa3b, v25
	v_exp_f32_e32 v193, v0
	v_mul_f32_e32 v0, 0xbfb8aa3b, v26
	v_exp_f32_e32 v208, v0
	v_mul_f32_e32 v0, 0xbfb8aa3b, v27
	v_mul_f32_e32 v60, 0xbfb8aa3b, v60
	v_mul_f32_e32 v56, 0xbfb8aa3b, v56
	v_mul_f32_e32 v52, 0xbfb8aa3b, v52
	v_mul_f32_e32 v48, 0xbfb8aa3b, v48
	v_mul_f32_e32 v44, 0xbfb8aa3b, v44
	v_mul_f32_e32 v40, 0xbfb8aa3b, v40
	v_mul_f32_e32 v36, 0xbfb8aa3b, v36
	v_mul_f32_e32 v28, 0xbfb8aa3b, v28
	v_mul_f32_e32 v20, 0xbfb8aa3b, v20
	v_mul_f32_e32 v16, 0xbfb8aa3b, v16
	v_mul_f32_e32 v8, 0xbfb8aa3b, v8
	v_mul_f32_e32 v4, 0xbfb8aa3b, v4
	v_exp_f32_e32 v192, v0
	v_mul_f32_e32 v0, 0xbfb8aa3b, v12
	v_exp_f32_e32 v148, v60
	v_mul_f32_e32 v60, 0xbfb8aa3b, v61
	v_exp_f32_e32 v144, v56
	v_mul_f32_e32 v56, 0xbfb8aa3b, v57
	v_exp_f32_e32 v221, v52
	v_mul_f32_e32 v52, 0xbfb8aa3b, v53
	v_exp_f32_e32 v219, v48
	v_mul_f32_e32 v48, 0xbfb8aa3b, v49
	v_exp_f32_e32 v140, v44
	v_mul_f32_e32 v44, 0xbfb8aa3b, v45
	v_exp_f32_e32 v136, v40
	v_mul_f32_e32 v40, 0xbfb8aa3b, v41
	v_exp_f32_e32 v217, v36
	v_mul_f32_e32 v36, 0xbfb8aa3b, v37
	v_exp_f32_e32 v215, v28
	v_mul_f32_e32 v28, 0xbfb8aa3b, v29
	v_exp_f32_e32 v132, v20
	v_mul_f32_e32 v20, 0xbfb8aa3b, v21
	v_exp_f32_e32 v128, v16
	v_mul_f32_e32 v16, 0xbfb8aa3b, v17
	v_exp_f32_e32 v213, v8
	v_mul_f32_e32 v8, 0xbfb8aa3b, v9
	v_exp_f32_e32 v211, v4
	v_mul_f32_e32 v4, 0xbfb8aa3b, v5
	v_exp_f32_e32 v207, v0
	v_mul_f32_e32 v0, 0xbfb8aa3b, v13
	v_exp_f32_e32 v149, v60
	v_mul_f32_e32 v60, 0xbfb8aa3b, v62
	v_exp_f32_e32 v145, v56
	v_mul_f32_e32 v56, 0xbfb8aa3b, v58
	v_exp_f32_e32 v205, v52
	v_mul_f32_e32 v52, 0xbfb8aa3b, v54
	v_exp_f32_e32 v203, v48
	v_mul_f32_e32 v48, 0xbfb8aa3b, v50
	v_exp_f32_e32 v141, v44
	v_mul_f32_e32 v44, 0xbfb8aa3b, v46
	v_exp_f32_e32 v137, v40
	v_mul_f32_e32 v40, 0xbfb8aa3b, v42
	v_exp_f32_e32 v201, v36
	v_mul_f32_e32 v36, 0xbfb8aa3b, v38
	v_exp_f32_e32 v199, v28
	v_mul_f32_e32 v28, 0xbfb8aa3b, v30
	v_exp_f32_e32 v133, v20
	v_mul_f32_e32 v20, 0xbfb8aa3b, v22
	v_exp_f32_e32 v129, v16
	v_mul_f32_e32 v16, 0xbfb8aa3b, v18
	v_exp_f32_e32 v197, v8
	v_mul_f32_e32 v8, 0xbfb8aa3b, v10
	v_exp_f32_e32 v195, v4
	v_mul_f32_e32 v4, 0xbfb8aa3b, v6
	v_exp_f32_e32 v170, v0
	v_mul_f32_e32 v0, 0xbfb8aa3b, v14
	v_exp_f32_e32 v146, v60
	v_mul_f32_e32 v60, 0xbfb8aa3b, v63
	v_exp_f32_e32 v142, v56
	v_mul_f32_e32 v56, 0xbfb8aa3b, v59
	v_exp_f32_e32 v220, v52
	v_mul_f32_e32 v52, 0xbfb8aa3b, v55
	v_exp_f32_e32 v218, v48
	v_mul_f32_e32 v48, 0xbfb8aa3b, v51
	v_exp_f32_e32 v138, v44
	v_mul_f32_e32 v44, 0xbfb8aa3b, v47
	v_exp_f32_e32 v134, v40
	v_mul_f32_e32 v40, 0xbfb8aa3b, v43
	v_exp_f32_e32 v216, v36
	v_mul_f32_e32 v36, 0xbfb8aa3b, v39
	v_exp_f32_e32 v214, v28
	v_mul_f32_e32 v28, 0xbfb8aa3b, v31
	v_exp_f32_e32 v130, v20
	v_mul_f32_e32 v20, 0xbfb8aa3b, v23
	v_exp_f32_e32 v126, v16
	v_mul_f32_e32 v16, 0xbfb8aa3b, v19
	v_exp_f32_e32 v212, v8
	v_mul_f32_e32 v8, 0xbfb8aa3b, v11
	v_exp_f32_e32 v210, v4
	v_mul_f32_e32 v4, 0xbfb8aa3b, v7
	v_exp_f32_e32 v206, v0
	v_mul_f32_e32 v0, 0xbfb8aa3b, v15
	v_exp_f32_e32 v147, v60
	v_exp_f32_e32 v143, v56
	v_exp_f32_e32 v204, v52
	v_exp_f32_e32 v202, v48
	v_exp_f32_e32 v139, v44
	v_exp_f32_e32 v135, v40
	v_exp_f32_e32 v200, v36
	v_exp_f32_e32 v198, v28
	v_exp_f32_e32 v131, v20
	v_exp_f32_e32 v127, v16
	v_exp_f32_e32 v196, v8
	v_exp_f32_e32 v194, v4
	v_exp_f32_e32 v169, v0
	s_cmp_eq_u32 s9, 1
	s_mov_b32 s15, 0xc90000
	s_movk_i32 s17, 0x280
	s_cselect_b32 s16, s15, 0xd10000
	s_cselect_b32 s15, 0x100, s60
	s_cselect_b32 s18, 0x180, s17
	s_cmp_eq_u32 s9, 0
	v_readfirstlane_b32 s21, v156
	s_cselect_b32 s16, 0xbd0000, s16
	s_cselect_b32 s18, 0, s18
	s_ashr_i32 s24, s21, 6
	s_lshl_b32 s25, s24, 5
	v_or_b32_e32 v4, s25, v157
	s_lshl_b32 s42, s18, 1
	v_ashrrev_i32_e32 v5, 31, v4
	v_lshl_add_u64 v[2:3], v[114:115], 0, s[42:43]
	v_lshlrev_b64 v[12:13], 11, v[4:5]
	s_lshl_b32 s20, s24, 12
	v_lshl_add_u64 v[4:5], v[2:3], 0, v[12:13]
	s_mov_b32 m0, s20
	s_barrier
; template <int NJ, bool SPLIT = false>
; __device__ __forceinline__ void gemm_tile_dma(const f16* __restrict__ A, int lda, const f16* __restrict__ Bt, int ldb,
;                                               int K, f32x4 (&acc)[4][NJ], f16* sA, const int tid) {
;     ...
;   __syncthreads();
;   D_STAGE(0, 0)
;   asm volatile("s_waitcnt vmcnt(0)" ::: "memory");
;   __syncthreads();
; __device__ __forceinline__ void phase_g2(const Params& p, int l, f16* smem) {
;     ...
;         f32x4 ab[4][2];
;         zero_acc<2>(ab);
;         gemm_tile_dma<2, true>(BR + (size_t)m0 * DM + aoff, DM, wo + (size_t)(n0 + h * 32) * kx, kx, kx, ab, sA, TIDX(p));
	global_load_lds_dwordx4 v[4:5], off
	v_lshl_add_u64 v[6:7], v[4:5], 0, s[66:67]
	s_or_b32 m0, s20, 0x400
	s_mov_b32 s17, 0
	global_load_lds_dwordx4 v[6:7], off
	v_lshl_add_u64 v[6:7], v[4:5], 0, s[92:93]
	s_or_b32 m0, s20, 0x800
	v_lshl_add_u64 v[0:1], v[68:69], 0, s[16:17]
	s_mul_hi_i32 s19, s15, s8
	s_mul_i32 s18, s15, s8
	s_lshl_b32 s36, s24, 4
	global_load_lds_dwordx4 v[6:7], off
	v_lshl_add_u64 v[4:5], v[4:5], 0, s[78:79]
	s_or_b32 m0, s20, 0xc00
	s_ashr_i32 s21, s21, 1
	global_load_lds_dwordx4 v[4:5], off
	v_lshl_add_u64 v[4:5], s[18:19], 1, v[0:1]
	s_lshl_b32 s18, s24, 11
	s_and_b32 s24, s36, 16
	s_and_b32 s37, s21, 0xffffffc0
	v_or_b32_e32 v6, s24, v157
	v_or_b32_e32 v8, s37, v6
	s_sub_i32 s21, s20, s18
	v_mad_i64_i32 v[6:7], s[18:19], v8, s15, 0
	s_add_i32 m0, s21, 0x4000
	v_lshl_add_u64 v[6:7], v[6:7], 1, v[4:5]
	global_load_lds_dwordx4 v[6:7], off
	v_or_b32_e32 v6, 8, v8
	v_mad_i64_i32 v[6:7], s[18:19], v6, s15, 0
	v_lshl_add_u64 v[4:5], v[6:7], 1, v[4:5]
	s_add_i32 m0, s21, 0x4400
	v_mov_b32_e32 v32, 0
	global_load_lds_dwordx4 v[4:5], off
	v_and_or_b32 v4, s25, 32, v158
	v_lshlrev_b32_e32 v15, 7, v4
	v_or_b32_e32 v4, s37, v163
	v_or_b32_e32 v5, s37, v158
	v_or_b32_e32 v4, s24, v4
	v_lshlrev_b32_e32 v14, 7, v5
	v_ashrrev_i32_e32 v5, 31, v4
	v_lshl_add_u64 v[6:7], v[4:5], 1, s[10:11]
	v_lshl_add_u64 v[4:5], v[78:79], 0, s[16:17]
	v_mad_u64_u32 v[8:9], s[18:19], v6, s15, v[4:5]
	v_or_b32_e32 v6, s37, v157
	v_or_b32_e32 v6, s24, v6
	v_mad_i32_i24 v9, v7, s15, v9
	v_ashrrev_i32_e32 v7, 31, v6
	v_lshl_add_u64 v[6:7], v[6:7], 1, s[10:11]
	s_waitcnt vmcnt(0)
	v_mad_u64_u32 v[10:11], s[18:19], v6, s15, v[4:5]
	v_mad_i32_i24 v11, v7, s15, v11
	v_lshl_add_u64 v[6:7], v[116:117], 0, s[42:43]
	v_lshl_add_u64 v[12:13], v[6:7], 0, v[12:13]
	s_mov_b32 s16, 64
	v_mov_b32_e32 v33, v32
	v_mov_b32_e32 v34, v32
	v_mov_b32_e32 v35, v32
	v_mov_b32_e32 v36, v32
	v_mov_b32_e32 v37, v32
	v_mov_b32_e32 v38, v32
	v_mov_b32_e32 v39, v32
	v_mov_b32_e32 v40, v32
	v_mov_b32_e32 v41, v32
	v_mov_b32_e32 v42, v32
	v_mov_b32_e32 v43, v32
	v_mov_b32_e32 v44, v32
	v_mov_b32_e32 v45, v32
	v_mov_b32_e32 v46, v32
	v_mov_b32_e32 v47, v32
	v_mov_b32_e32 v48, v32
	v_mov_b32_e32 v49, v32
	v_mov_b32_e32 v50, v32
	v_mov_b32_e32 v51, v32
	v_mov_b32_e32 v52, v32
	v_mov_b32_e32 v53, v32
	v_mov_b32_e32 v54, v32
	v_mov_b32_e32 v55, v32
	v_mov_b32_e32 v56, v32
	v_mov_b32_e32 v57, v32
	v_mov_b32_e32 v58, v32
	v_mov_b32_e32 v59, v32
	v_mov_b32_e32 v60, v32
	v_mov_b32_e32 v61, v32
	v_mov_b32_e32 v62, v32
	v_mov_b32_e32 v63, v32
	s_waitcnt vmcnt(0) lgkmcnt(0)
	s_barrier
	s_setprio 1
	s_bitcmp1_b32 s95, 8
	s_cbranch_scc0 .Lprio_g2_1121
	s_setprio 2

; template <int NJ, bool SPLIT = false>
; __device__ __forceinline__ void gemm_tile_dma(const f16* __restrict__ A, int lda, const f16* __restrict__ Bt, int ldb,
;                                               int K, f32x4 (&acc)[4][NJ], f16* sA, const int tid) {
;     ...
;   __syncthreads();
;   D_STAGE(0, 0)
;   asm volatile("s_waitcnt vmcnt(0)" ::: "memory");
;   __syncthreads();
; __device__ __forceinline__ void phase_g2(const Params& p, int l, f16* smem) {
;     ...
;       for (int h = 0; h < 2; ++h) {
;         f32x4 ab[4][2];
;         zero_acc<2>(ab);
;         gemm_tile_dma<2, true>(BR + (size_t)m0 * DM + aoff, DM, wo + (size_t)(n0 + h * 32) * kx, kx, kx, ab, sA, TIDX(p));
.LBB0_1123:
	s_setprio 0
	v_readfirstlane_b32 s19, v156
	s_ashr_i32 s20, s19, 6
	s_lshl_b32 s21, s20, 5
	v_or_b32_e32 v8, s21, v157
	v_ashrrev_i32_e32 v9, 31, v8
	v_lshlrev_b64 v[8:9], 11, v[8:9]
	s_lshl_b32 s18, s20, 12
	v_lshl_add_u64 v[2:3], v[2:3], 0, v[8:9]
	s_mov_b32 m0, s18
	s_barrier
	global_load_lds_dwordx4 v[2:3], off
	v_lshl_add_u64 v[10:11], v[2:3], 0, s[66:67]
	s_or_b32 m0, s18, 0x400
	s_mul_hi_i32 s17, s15, s7
	s_mul_i32 s16, s15, s7
	s_lshl_b32 s24, s20, 4
	global_load_lds_dwordx4 v[10:11], off
	v_lshl_add_u64 v[10:11], v[2:3], 0, s[92:93]
	s_or_b32 m0, s18, 0x800
	s_ashr_i32 s19, s19, 1
	global_load_lds_dwordx4 v[10:11], off
	v_lshl_add_u64 v[2:3], v[2:3], 0, s[78:79]
	s_or_b32 m0, s18, 0xc00
	v_lshl_add_u64 v[0:1], s[16:17], 1, v[0:1]
	s_lshl_b32 s16, s20, 11
	s_and_b32 s20, s24, 16
	s_and_b32 s25, s19, 0xffffffc0
	global_load_lds_dwordx4 v[2:3], off
	v_or_b32_e32 v2, s20, v157
	v_or_b32_e32 v10, s25, v2
	s_sub_i32 s19, s18, s16
	v_mad_i64_i32 v[2:3], s[16:17], v10, s15, 0
	s_add_i32 m0, s19, 0x4000
	v_lshl_add_u64 v[2:3], v[2:3], 1, v[0:1]
	global_load_lds_dwordx4 v[2:3], off
	v_or_b32_e32 v2, 8, v10
	v_mad_i64_i32 v[2:3], s[16:17], v2, s15, 0
	v_lshl_add_u64 v[0:1], v[2:3], 1, v[0:1]
	s_add_i32 m0, s19, 0x4400
	v_lshl_add_u64 v[154:155], v[6:7], 0, v[8:9]
	global_load_lds_dwordx4 v[0:1], off
	v_and_or_b32 v0, s21, 32, v158
	v_lshlrev_b32_e32 v223, 7, v0
	v_or_b32_e32 v0, s25, v163
	v_or_b32_e32 v1, s25, v158
	v_or_b32_e32 v0, s20, v0
	v_lshlrev_b32_e32 v222, 7, v1
	v_ashrrev_i32_e32 v1, 31, v0
	v_lshl_add_u64 v[0:1], v[0:1], 1, s[12:13]
	v_mad_u64_u32 v[150:151], s[16:17], v0, s15, v[4:5]
	v_mov_b32_e32 v0, v151
	v_mad_u64_u32 v[0:1], s[16:17], v1, s15, v[0:1]
	v_mov_b32_e32 v151, v0
	v_or_b32_e32 v0, s25, v157
	v_or_b32_e32 v0, s20, v0
	v_ashrrev_i32_e32 v1, 31, v0
	v_lshl_add_u64 v[0:1], v[0:1], 1, s[12:13]
	v_mad_u64_u32 v[152:153], s[16:17], v0, s15, v[4:5]
	v_mov_b32_e32 v0, v153
	s_waitcnt vmcnt(0)
	v_mad_u64_u32 v[0:1], s[16:17], v1, s15, v[0:1]
	v_mov_b32_e32 v153, v0
	v_mov_b32_e32 v0, 0
	s_mov_b32 s20, 0
	s_mov_b32 s21, 64
	v_mov_b32_e32 v1, v0
	v_mov_b32_e32 v2, v0
	v_mov_b32_e32 v3, v0
	v_mov_b32_e32 v4, v0
	v_mov_b32_e32 v5, v0
	v_mov_b32_e32 v6, v0
	v_mov_b32_e32 v7, v0
	v_mov_b32_e32 v8, v0
	v_mov_b32_e32 v9, v0
	v_mov_b32_e32 v10, v0
	v_mov_b32_e32 v11, v0
	v_mov_b32_e32 v12, v0
	v_mov_b32_e32 v13, v0
	v_mov_b32_e32 v14, v0
	v_mov_b32_e32 v15, v0
	v_mov_b32_e32 v16, v0
	v_mov_b32_e32 v17, v0
	v_mov_b32_e32 v18, v0
	v_mov_b32_e32 v19, v0
	v_mov_b32_e32 v20, v0
	v_mov_b32_e32 v21, v0
	v_mov_b32_e32 v22, v0
	v_mov_b32_e32 v23, v0
	v_mov_b32_e32 v24, v0
	v_mov_b32_e32 v25, v0
	v_mov_b32_e32 v26, v0
	v_mov_b32_e32 v27, v0
	v_mov_b32_e32 v28, v0
	v_mov_b32_e32 v29, v0
	v_mov_b32_e32 v30, v0
	v_mov_b32_e32 v31, v0
	s_waitcnt vmcnt(0) lgkmcnt(0)
	s_barrier
	s_setprio 1
	s_bitcmp1_b32 s95, 8
	s_cbranch_scc0 .Lprio_g2_1125
	s_setprio 2
